# static s_setprio 1 for waves 0-3 in the hyena MFMA loop and the GQA attention step loop
# baseline (speedup 1.0000x reference)
.Lhy_gw_short:
	s_waitcnt vmcnt(0)
	ds_write_b128 v6, v[72:75]
	ds_write_b128 v6, v[76:79] offset:1280
	ds_write_b128 v6, v[80:83] offset:2560
	ds_write_b128 v6, v[84:87] offset:3840
	s_or_b64 exec, exec, s[14:15]
	v_cmp_gt_i32_e32 vcc, 8, v34
	s_and_saveexec_b64 s[14:15], vcc
	v_lshl_add_u32 v0, v34, 2, 0
	v_add_u32_e32 v0, 0x1a000, v0
	ds_write_b32 v0, v1
	s_or_b64 exec, exec, s[14:15]
	s_lshr_b32 s6, s7, 5
	s_and_b64 s[4:5], s[40:41], exec
	s_cselect_b32 s10, 3, 5
	s_add_i32 s11, s6, -1
	v_and_b32_e32 v2, 31, v34
	s_and_b64 s[4:5], s[40:41], exec
	s_cselect_b32 s4, 8, 10
	v_lshrrev_b32_e32 v0, s10, v2
	v_lshlrev_b32_e32 v38, s4, v0
	v_or_b32_e32 v0, 32, v2
	v_lshl_add_u32 v3, s7, 2, v5
	v_lshlrev_b32_e32 v2, 1, v2
	v_bitop3_b32 v37, v34, s11, 31 bitop3:0x80
	v_lshrrev_b32_e32 v0, s10, v0
	v_sub_u32_e32 v2, v3, v2
	v_readlane_b32 s5, v253, 18
	v_lshlrev_b32_e32 v0, s4, v0
	v_lshlrev_b32_e32 v4, 1, v0
	v_add_u32_e32 v40, s5, v2
	v_add_u32_e32 v2, s6, v37
	v_lshl_add_u32 v3, v2, 6, v5
	v_lshrrev_b32_e32 v36, 5, v8
	s_lshr_b32 s4, s7, 4
	v_add3_u32 v41, v3, v4, 0
	v_lshlrev_b32_e32 v4, 1, v38
	v_mov_b32_e32 v18, 0
	v_lshlrev_b32_e32 v39, 4, v36
	s_add_i32 s7, s4, -1
	v_add3_u32 v42, v3, v4, 0
	v_lshrrev_b32_e32 v44, 5, v0
	v_lshrrev_b32_e32 v45, 5, v38
	v_add_u32_e32 v44, v44, v2
	v_add_u32_e32 v45, v45, v2
	v_lshlrev_b32_e32 v44, 4, v44
	v_lshlrev_b32_e32 v45, 4, v45
	v_lshl_add_u32 v44, v35, 10, v44
	v_lshl_add_u32 v45, v35, 10, v45
	v_add_u32_e32 v41, v41, v44
	v_add_u32_e32 v42, v42, v45
	v_add_u32_e32 v43, -1, v2
	v_mov_b32_e32 v19, v18
	v_mov_b32_e32 v20, v18
	v_mov_b32_e32 v21, v18
	v_mov_b32_e32 v22, v18
	v_mov_b32_e32 v23, v18
	v_mov_b32_e32 v24, v18
	v_mov_b32_e32 v25, v18
	v_mov_b32_e32 v26, v18
	v_mov_b32_e32 v27, v18
	v_mov_b32_e32 v28, v18
	v_mov_b32_e32 v29, v18
	v_mov_b32_e32 v30, v18
	v_mov_b32_e32 v31, v18
	v_mov_b32_e32 v32, v18
	v_mov_b32_e32 v33, v18
	v_mov_b32_e32 v2, v18
	v_mov_b32_e32 v3, v18
	v_mov_b32_e32 v4, v18
	v_mov_b32_e32 v5, v18
	v_mov_b32_e32 v6, v18
	v_mov_b32_e32 v7, v18
	v_mov_b32_e32 v8, v18
	v_mov_b32_e32 v9, v18
	v_mov_b32_e32 v10, v18
	v_mov_b32_e32 v11, v18
	v_mov_b32_e32 v12, v18
	v_mov_b32_e32 v13, v18
	v_mov_b32_e32 v14, v18
	v_mov_b32_e32 v15, v18
	v_mov_b32_e32 v16, v18
	v_mov_b32_e32 v17, v18
	s_waitcnt lgkmcnt(0)
	s_barrier
	v_readfirstlane_b32 s96, v35
	s_nop 3
	s_cmp_ge_u32 s96, 4
	s_cbranch_scc1 .Lhy_prio_done
	s_setprio 1
.Lhy_prio_done:
	v_add_u32_e32 v124, v40, v39
	v_and_b32_e32 v124, 2, v124
	v_lshlrev_b32_e32 v124, 3, v124
	s_add_i32 s4, 0, 0x1a000
	v_mov_b32_e32 v54, s4
	v_add_u32_e32 v52, v40, v39
	v_and_b32_e32 v52, -4, v52
	s_nop 0
	ds_read2_b32 v[104:105], v52 offset1:1
	ds_read2_b32 v[106:107], v52 offset0:2 offset1:3
	ds_read_b32 v108, v52 offset:16
	v_cmp_lt_i32_e32 vcc, -1, v43
	v_cmp_gt_i32_e64 s[40:41], s6, v43
	v_add_u32_e32 v53, v42, v39
	v_add_u32_e32 v55, v41, v39
	s_and_b64 vcc, vcc, s[40:41]
	v_add_u32_e32 v120, 0xffb0, v53
	v_add_u32_e32 v121, 0xffb0, v55
	v_add_u32_e32 v122, 0xffd0, v53
	v_add_u32_e32 v123, 0xffd0, v55
	v_cndmask_b32_e32 v120, v54, v120, vcc
	v_cndmask_b32_e32 v121, v54, v121, vcc
	v_cndmask_b32_e32 v122, v54, v122, vcc
	v_cndmask_b32_e32 v123, v54, v123, vcc
	ds_read_b128 v[48:51], v120
	ds_read_b128 v[92:95], v121
	ds_read_b128 v[96:99], v122
	ds_read_b128 v[100:103], v123
	ds_read2_b32 v[112:113], v52 offset0:8 offset1:9
	ds_read2_b32 v[114:115], v52 offset0:10 offset1:11
	ds_read_b32 v116, v52 offset:48
	v_subrev_u32_e32 v40, 64, v40
	v_subrev_u32_e32 v41, 0x50, v41
	v_subrev_u32_e32 v42, 0x50, v42
	v_add_u32_e32 v43, -1, v43
	s_waitcnt lgkmcnt(0)
	v_alignbit_b32 v44, v105, v104, v124
	v_alignbit_b32 v45, v106, v105, v124
	v_alignbit_b32 v46, v107, v106, v124
	v_alignbit_b32 v47, v108, v107, v124
	v_alignbit_b32 v88, v113, v112, v124
	v_alignbit_b32 v89, v114, v113, v124
	v_alignbit_b32 v90, v115, v114, v124
	v_alignbit_b32 v91, v116, v115, v124
.LBB0_532:
	v_mfma_f32_32x32x16_bf16 v[18:33], v[44:47], v[48:51], v[18:33]
	v_mfma_f32_32x32x16_bf16 v[2:17], v[44:47], v[92:95], v[2:17]
	v_mfma_f32_32x32x16_bf16 v[18:33], v[88:91], v[96:99], v[18:33]
	v_mfma_f32_32x32x16_bf16 v[2:17], v[88:91], v[100:103], v[2:17]
	s_add_i32 s7, s7, -1
	v_add_u32_e32 v52, v40, v39
	v_and_b32_e32 v52, -4, v52
	s_nop 0
	ds_read2_b32 v[104:105], v52 offset1:1
	ds_read2_b32 v[106:107], v52 offset0:2 offset1:3
	ds_read_b32 v108, v52 offset:16
	v_cmp_lt_i32_e32 vcc, -1, v43
	v_cmp_gt_i32_e64 s[40:41], s6, v43
	v_add_u32_e32 v53, v42, v39
	v_add_u32_e32 v55, v41, v39
	s_and_b64 vcc, vcc, s[40:41]
	v_add_u32_e32 v120, 0xffb0, v53
	v_add_u32_e32 v121, 0xffb0, v55
	v_add_u32_e32 v122, 0xffd0, v53
	v_add_u32_e32 v123, 0xffd0, v55
	v_cndmask_b32_e32 v120, v54, v120, vcc
	v_cndmask_b32_e32 v121, v54, v121, vcc
	v_cndmask_b32_e32 v122, v54, v122, vcc
	v_cndmask_b32_e32 v123, v54, v123, vcc
	ds_read_b128 v[48:51], v120
	ds_read_b128 v[92:95], v121
	ds_read_b128 v[96:99], v122
	ds_read_b128 v[100:103], v123
	ds_read2_b32 v[112:113], v52 offset0:8 offset1:9
	ds_read2_b32 v[114:115], v52 offset0:10 offset1:11
	ds_read_b32 v116, v52 offset:48
	v_subrev_u32_e32 v40, 64, v40
	v_subrev_u32_e32 v41, 0x50, v41
	v_subrev_u32_e32 v42, 0x50, v42
	v_add_u32_e32 v43, -1, v43
	s_waitcnt lgkmcnt(0)
	v_alignbit_b32 v44, v105, v104, v124
	v_alignbit_b32 v45, v106, v105, v124
	v_alignbit_b32 v46, v107, v106, v124
	v_alignbit_b32 v47, v108, v107, v124
	v_alignbit_b32 v88, v113, v112, v124
	v_alignbit_b32 v89, v114, v113, v124
	v_alignbit_b32 v90, v115, v114, v124
	v_alignbit_b32 v91, v116, v115, v124
	s_cmp_lg_u32 s7, 0
	s_cbranch_scc1 .LBB0_532
	s_setprio 0
	s_barrier
	v_lshlrev_b32_e32 v37, 5, v37
	v_lshlrev_b32_e32 v36, 2, v36
	v_add_u32_e32 v38, v38, v37
	v_lshl_add_u32 v35, v35, 1, 0
	v_or_b32_e32 v38, v38, v36
	v_bfe_u32 v39, v18, 16, 1
	v_add3_u32 v18, v18, v39, s27
	v_lshrrev_b32_e32 v56, 5, v38
	v_lshl_add_u32 v38, v38, 4, v35
	v_lshl_add_u32 v38, v56, 4, v38
	ds_write_b16_d16_hi v38, v18
	v_bfe_u32 v18, v19, 16, 1
	v_add3_u32 v18, v19, v18, s27
	ds_write_b16_d16_hi v38, v18 offset:16
	v_bfe_u32 v18, v20, 16, 1
	v_add3_u32 v18, v20, v18, s27
	ds_write_b16_d16_hi v38, v18 offset:32
	v_bfe_u32 v18, v21, 16, 1
	v_add3_u32 v18, v21, v18, s27
	ds_write_b16_d16_hi v38, v18 offset:48
	v_bfe_u32 v18, v22, 16, 1
	v_add3_u32 v18, v22, v18, s27
	ds_write_b16_d16_hi v38, v18 offset:128
	v_bfe_u32 v18, v23, 16, 1
	v_add3_u32 v18, v23, v18, s27
	ds_write_b16_d16_hi v38, v18 offset:144
	v_bfe_u32 v18, v24, 16, 1
	v_add3_u32 v18, v24, v18, s27
	ds_write_b16_d16_hi v38, v18 offset:160
	v_bfe_u32 v18, v25, 16, 1
	v_add3_u32 v18, v25, v18, s27
	ds_write_b16_d16_hi v38, v18 offset:176
	v_bfe_u32 v18, v26, 16, 1
	v_add3_u32 v18, v26, v18, s27
	ds_write_b16_d16_hi v38, v18 offset:256
	v_bfe_u32 v18, v27, 16, 1
	v_add3_u32 v18, v27, v18, s27
	ds_write_b16_d16_hi v38, v18 offset:272
	v_bfe_u32 v18, v28, 16, 1
	v_add3_u32 v18, v28, v18, s27
	ds_write_b16_d16_hi v38, v18 offset:288
	v_bfe_u32 v18, v29, 16, 1
	v_add3_u32 v18, v29, v18, s27
	ds_write_b16_d16_hi v38, v18 offset:304
	v_bfe_u32 v18, v30, 16, 1
	v_add3_u32 v18, v30, v18, s27
	ds_write_b16_d16_hi v38, v18 offset:384
	v_bfe_u32 v18, v31, 16, 1
	v_add3_u32 v18, v31, v18, s27
	ds_write_b16_d16_hi v38, v18 offset:400
	v_bfe_u32 v18, v32, 16, 1
	v_add3_u32 v18, v32, v18, s27
	ds_write_b16_d16_hi v38, v18 offset:416
	v_bfe_u32 v18, v33, 16, 1
	v_add3_u32 v18, v33, v18, s27
	v_add_u32_e32 v0, v0, v37
	ds_write_b16_d16_hi v38, v18 offset:432
	v_or_b32_e32 v0, v0, v36
	v_bfe_u32 v18, v2, 16, 1
	v_add3_u32 v2, v2, v18, s27
	v_lshrrev_b32_e32 v57, 5, v0
	v_lshl_add_u32 v0, v0, 4, v35
	v_lshl_add_u32 v0, v57, 4, v0
	ds_write_b16_d16_hi v0, v2
	v_bfe_u32 v2, v3, 16, 1
	v_add3_u32 v2, v3, v2, s27
	ds_write_b16_d16_hi v0, v2 offset:16
	v_bfe_u32 v2, v4, 16, 1
	v_add3_u32 v2, v4, v2, s27
	ds_write_b16_d16_hi v0, v2 offset:32
	v_bfe_u32 v2, v5, 16, 1
	v_add3_u32 v2, v5, v2, s27
	ds_write_b16_d16_hi v0, v2 offset:48
	v_bfe_u32 v2, v6, 16, 1
	v_add3_u32 v2, v6, v2, s27
	ds_write_b16_d16_hi v0, v2 offset:128
	v_bfe_u32 v2, v7, 16, 1
	v_add3_u32 v2, v7, v2, s27
	ds_write_b16_d16_hi v0, v2 offset:144
	v_bfe_u32 v2, v8, 16, 1
	v_add3_u32 v2, v8, v2, s27
	ds_write_b16_d16_hi v0, v2 offset:160
	v_bfe_u32 v2, v9, 16, 1
	v_add3_u32 v2, v9, v2, s27
	ds_write_b16_d16_hi v0, v2 offset:176
	v_bfe_u32 v2, v10, 16, 1
	v_add3_u32 v2, v10, v2, s27
	ds_write_b16_d16_hi v0, v2 offset:256
	v_bfe_u32 v2, v11, 16, 1
	v_add3_u32 v2, v11, v2, s27
	ds_write_b16_d16_hi v0, v2 offset:272
	v_bfe_u32 v2, v12, 16, 1
	v_add3_u32 v2, v12, v2, s27
	ds_write_b16_d16_hi v0, v2 offset:288
	v_bfe_u32 v2, v13, 16, 1
	v_add3_u32 v2, v13, v2, s27
	ds_write_b16_d16_hi v0, v2 offset:304
	v_bfe_u32 v2, v14, 16, 1
	v_add3_u32 v2, v14, v2, s27
	ds_write_b16_d16_hi v0, v2 offset:384
	v_bfe_u32 v2, v15, 16, 1
	v_add3_u32 v2, v15, v2, s27
	ds_write_b16_d16_hi v0, v2 offset:400
	v_bfe_u32 v2, v16, 16, 1
	v_add3_u32 v2, v16, v2, s27
	ds_write_b16_d16_hi v0, v2 offset:416
	v_bfe_u32 v2, v17, 16, 1
	s_movk_i32 s4, 0x800
	v_add3_u32 v2, v17, v2, s27
	v_cmp_gt_i32_e32 vcc, s4, v34
	ds_write_b16_d16_hi v0, v2 offset:432
	s_waitcnt lgkmcnt(0)
	s_barrier
	s_and_saveexec_b64 s[40:41], vcc
	s_mov_b64 s[10:11], 0x100000
	s_cbranch_execz .LBB0_497
	s_add_i32 s4, s38, s3
	s_ashr_i32 s5, s4, 31
	s_lshl_b64 s[4:5], s[4:5], 2
	s_add_u32 s4, s42, s4
	s_addc_u32 s5, s43, s5
	global_load_dwordx4 v[2:5], v1, s[4:5] offset:16
	global_load_dwordx4 v[6:9], v1, s[4:5]
	s_ashr_i32 s39, s38, 31
	v_add_u32_e32 v12, s44, v34
	s_lshl_b64 s[4:5], s[38:39], 1
	v_readlane_b32 s6, v253, 50
	v_ashrrev_i32_e32 v13, 31, v12
	v_readlane_b32 s7, v253, 51
	s_add_u32 s6, s6, s4
	v_lshlrev_b64 v[10:11], 11, v[12:13]
	s_addc_u32 s7, s7, s5
	v_lshl_add_u64 v[10:11], s[6:7], 0, v[10:11]
	v_readlane_b32 s6, v254, 49
	v_readlane_b32 s7, v254, 50
	s_add_u32 s4, s6, s4
	v_lshlrev_b64 v[12:13], 10, v[12:13]
	s_addc_u32 s5, s7, s5
	v_add_u32_e32 v0, 0xfffffe00, v34
	v_lshl_add_u32 v14, v34, 4, 0
	v_lshrrev_b32_e32 v15, 5, v34
	v_lshl_add_u32 v14, v15, 4, v14
	v_lshl_add_u64 v[12:13], s[4:5], 0, v[12:13]
	s_mov_b64 s[38:39], 0
	s_mov_b64 s[4:5], 0x80000
	global_load_dwordx4 v[56:59], v[12:13], off
	v_add_co_u32_e32 v24, vcc, 0x600000, v12
	s_nop 1
	v_addc_co_u32_e32 v25, vcc, 0, v13, vcc
	global_load_dwordx4 v[72:75], v[24:25], off
	ds_read_b128 v[88:91], v14
	v_lshl_add_u64 v[12:13], v[12:13], 0, s[4:5]
	global_load_dwordx4 v[60:63], v[12:13], off
	v_add_co_u32_e32 v24, vcc, 0x600000, v12
	s_nop 1
	v_addc_co_u32_e32 v25, vcc, 0, v13, vcc
	global_load_dwordx4 v[76:79], v[24:25], off
	ds_read_b128 v[92:95], v14 offset:8448
	v_lshl_add_u64 v[12:13], v[12:13], 0, s[4:5]
	global_load_dwordx4 v[64:67], v[12:13], off
	v_add_co_u32_e32 v24, vcc, 0x600000, v12
	s_nop 1
	v_addc_co_u32_e32 v25, vcc, 0, v13, vcc
	global_load_dwordx4 v[80:83], v[24:25], off
	ds_read_b128 v[96:99], v14 offset:16896
	v_lshl_add_u64 v[12:13], v[12:13], 0, s[4:5]
	global_load_dwordx4 v[68:71], v[12:13], off
	v_add_co_u32_e32 v24, vcc, 0x600000, v12
	s_nop 1
	v_addc_co_u32_e32 v25, vcc, 0, v13, vcc
	global_load_dwordx4 v[84:87], v[24:25], off
	ds_read_b128 v[100:103], v14 offset:25344
	v_lshl_add_u64 v[12:13], v[12:13], 0, s[4:5]
	s_waitcnt vmcnt(6) lgkmcnt(3)
	v_mov_b32_e32 v16, v88
	v_mov_b32_e32 v17, v89
	v_mov_b32_e32 v18, v90
	v_mov_b32_e32 v19, v91
	v_mov_b32_e32 v20, v56
	v_mov_b32_e32 v21, v57
	v_mov_b32_e32 v22, v58
	v_mov_b32_e32 v23, v59
	v_mov_b32_e32 v24, v72
	v_mov_b32_e32 v25, v73
	v_mov_b32_e32 v26, v74
	v_mov_b32_e32 v27, v75
	v_and_b32_e32 v31, 0xffff0000, v16
	v_lshlrev_b32_e32 v30, 16, v16
	v_and_b32_e32 v29, 0xffff0000, v20
	v_lshlrev_b32_e32 v28, 16, v20
	v_lshlrev_b32_e32 v20, 16, v17
	v_and_b32_e32 v33, 0xffff0000, v24
	v_lshlrev_b32_e32 v32, 16, v24
	v_pk_fma_f32 v[30:31], v[6:7], v[32:33], v[30:31]
	v_lshlrev_b32_e32 v16, 16, v25
	v_pk_mul_f32 v[28:29], v[30:31], v[28:29]
	v_and_b32_e32 v31, 0xffff0000, v21
	v_lshlrev_b32_e32 v30, 16, v21
	v_and_b32_e32 v21, 0xffff0000, v17
	v_and_b32_e32 v17, 0xffff0000, v25
	v_pk_fma_f32 v[16:17], v[8:9], v[16:17], v[20:21]
	v_and_b32_e32 v25, 0xffff0000, v18
	v_pk_mul_f32 v[20:21], v[16:17], v[30:31]
	v_lshlrev_b32_e32 v24, 16, v18
	v_and_b32_e32 v31, 0xffff0000, v26
	v_lshlrev_b32_e32 v30, 16, v26
	v_and_b32_e32 v17, 0xffff0000, v22
	v_lshlrev_b32_e32 v16, 16, v22
	v_pk_fma_f32 v[24:25], v[2:3], v[30:31], v[24:25]
	v_lshlrev_b32_e32 v22, 16, v19
	v_pk_mul_f32 v[24:25], v[24:25], v[16:17]
	v_and_b32_e32 v17, 0xffff0000, v23
	v_lshlrev_b32_e32 v16, 16, v23
	v_and_b32_e32 v23, 0xffff0000, v19
	v_and_b32_e32 v19, 0xffff0000, v27
	v_lshlrev_b32_e32 v18, 16, v27
	v_pk_fma_f32 v[18:19], v[4:5], v[18:19], v[22:23]
	s_nop 0
	v_pk_mul_f32 v[22:23], v[18:19], v[16:17]
	v_cvt_pk_bf16_f32 v16, v28, v29
	v_cvt_pk_bf16_f32 v17, v20, v21
	v_cvt_pk_bf16_f32 v18, v24, v25
	v_cvt_pk_bf16_f32 v19, v22, v23
	global_store_dwordx4 v[10:11], v[16:19], off
	v_lshl_add_u64 v[10:11], v[10:11], 0, s[10:11]
	s_nop 1
	s_waitcnt vmcnt(5) lgkmcnt(2)
	v_mov_b32_e32 v16, v92
	v_mov_b32_e32 v17, v93
	v_mov_b32_e32 v18, v94
	v_mov_b32_e32 v19, v95
	v_mov_b32_e32 v20, v60
	v_mov_b32_e32 v21, v61
	v_mov_b32_e32 v22, v62
	v_mov_b32_e32 v23, v63
	v_mov_b32_e32 v24, v76
	v_mov_b32_e32 v25, v77
	v_mov_b32_e32 v26, v78
	v_mov_b32_e32 v27, v79
	v_and_b32_e32 v31, 0xffff0000, v16
	v_lshlrev_b32_e32 v30, 16, v16
	v_and_b32_e32 v29, 0xffff0000, v20
	v_lshlrev_b32_e32 v28, 16, v20
	v_lshlrev_b32_e32 v20, 16, v17
	v_and_b32_e32 v33, 0xffff0000, v24
	v_lshlrev_b32_e32 v32, 16, v24
	v_pk_fma_f32 v[30:31], v[6:7], v[32:33], v[30:31]
	v_lshlrev_b32_e32 v16, 16, v25
	v_pk_mul_f32 v[28:29], v[30:31], v[28:29]
	v_and_b32_e32 v31, 0xffff0000, v21
	v_lshlrev_b32_e32 v30, 16, v21
	v_and_b32_e32 v21, 0xffff0000, v17
	v_and_b32_e32 v17, 0xffff0000, v25
	v_pk_fma_f32 v[16:17], v[8:9], v[16:17], v[20:21]
	v_and_b32_e32 v25, 0xffff0000, v18
	v_pk_mul_f32 v[20:21], v[16:17], v[30:31]
	v_lshlrev_b32_e32 v24, 16, v18
	v_and_b32_e32 v31, 0xffff0000, v26
	v_lshlrev_b32_e32 v30, 16, v26
	v_and_b32_e32 v17, 0xffff0000, v22
	v_lshlrev_b32_e32 v16, 16, v22
	v_pk_fma_f32 v[24:25], v[2:3], v[30:31], v[24:25]
	v_lshlrev_b32_e32 v22, 16, v19
	v_pk_mul_f32 v[24:25], v[24:25], v[16:17]
	v_and_b32_e32 v17, 0xffff0000, v23
	v_lshlrev_b32_e32 v16, 16, v23
	v_and_b32_e32 v23, 0xffff0000, v19
	v_and_b32_e32 v19, 0xffff0000, v27
	v_lshlrev_b32_e32 v18, 16, v27
	v_pk_fma_f32 v[18:19], v[4:5], v[18:19], v[22:23]
	s_nop 0
	v_pk_mul_f32 v[22:23], v[18:19], v[16:17]
	v_cvt_pk_bf16_f32 v16, v28, v29
	v_cvt_pk_bf16_f32 v17, v20, v21
	v_cvt_pk_bf16_f32 v18, v24, v25
	v_cvt_pk_bf16_f32 v19, v22, v23
	global_store_dwordx4 v[10:11], v[16:19], off
	v_lshl_add_u64 v[10:11], v[10:11], 0, s[10:11]
	s_nop 1
	s_waitcnt vmcnt(4) lgkmcnt(1)
	v_mov_b32_e32 v16, v96
	v_mov_b32_e32 v17, v97
	v_mov_b32_e32 v18, v98
	v_mov_b32_e32 v19, v99
	v_mov_b32_e32 v20, v64
	v_mov_b32_e32 v21, v65
	v_mov_b32_e32 v22, v66
	v_mov_b32_e32 v23, v67
	v_mov_b32_e32 v24, v80
	v_mov_b32_e32 v25, v81
	v_mov_b32_e32 v26, v82
	v_mov_b32_e32 v27, v83
	v_and_b32_e32 v31, 0xffff0000, v16
	v_lshlrev_b32_e32 v30, 16, v16
	v_and_b32_e32 v29, 0xffff0000, v20
	v_lshlrev_b32_e32 v28, 16, v20
	v_lshlrev_b32_e32 v20, 16, v17
	v_and_b32_e32 v33, 0xffff0000, v24
	v_lshlrev_b32_e32 v32, 16, v24
	v_pk_fma_f32 v[30:31], v[6:7], v[32:33], v[30:31]
	v_lshlrev_b32_e32 v16, 16, v25
	v_pk_mul_f32 v[28:29], v[30:31], v[28:29]
	v_and_b32_e32 v31, 0xffff0000, v21
	v_lshlrev_b32_e32 v30, 16, v21
	v_and_b32_e32 v21, 0xffff0000, v17
	v_and_b32_e32 v17, 0xffff0000, v25
	v_pk_fma_f32 v[16:17], v[8:9], v[16:17], v[20:21]
	v_and_b32_e32 v25, 0xffff0000, v18
	v_pk_mul_f32 v[20:21], v[16:17], v[30:31]
	v_lshlrev_b32_e32 v24, 16, v18
	v_and_b32_e32 v31, 0xffff0000, v26
	v_lshlrev_b32_e32 v30, 16, v26
	v_and_b32_e32 v17, 0xffff0000, v22
	v_lshlrev_b32_e32 v16, 16, v22
	v_pk_fma_f32 v[24:25], v[2:3], v[30:31], v[24:25]
	v_lshlrev_b32_e32 v22, 16, v19
	v_pk_mul_f32 v[24:25], v[24:25], v[16:17]
	v_and_b32_e32 v17, 0xffff0000, v23
	v_lshlrev_b32_e32 v16, 16, v23
	v_and_b32_e32 v23, 0xffff0000, v19
	v_and_b32_e32 v19, 0xffff0000, v27
	v_lshlrev_b32_e32 v18, 16, v27
	v_pk_fma_f32 v[18:19], v[4:5], v[18:19], v[22:23]
	s_nop 0
	v_pk_mul_f32 v[22:23], v[18:19], v[16:17]
	v_cvt_pk_bf16_f32 v16, v28, v29
	v_cvt_pk_bf16_f32 v17, v20, v21
	v_cvt_pk_bf16_f32 v18, v24, v25
	v_cvt_pk_bf16_f32 v19, v22, v23
	global_store_dwordx4 v[10:11], v[16:19], off
	v_lshl_add_u64 v[10:11], v[10:11], 0, s[10:11]
	s_nop 1
	s_waitcnt vmcnt(3) lgkmcnt(0)
	v_mov_b32_e32 v16, v100
	v_mov_b32_e32 v17, v101
	v_mov_b32_e32 v18, v102
	v_mov_b32_e32 v19, v103
	v_mov_b32_e32 v20, v68
	v_mov_b32_e32 v21, v69
	v_mov_b32_e32 v22, v70
	v_mov_b32_e32 v23, v71
	v_mov_b32_e32 v24, v84
	v_mov_b32_e32 v25, v85
	v_mov_b32_e32 v26, v86
	v_mov_b32_e32 v27, v87
	v_and_b32_e32 v31, 0xffff0000, v16
	v_lshlrev_b32_e32 v30, 16, v16
	v_and_b32_e32 v29, 0xffff0000, v20
	v_lshlrev_b32_e32 v28, 16, v20
	v_lshlrev_b32_e32 v20, 16, v17
	v_and_b32_e32 v33, 0xffff0000, v24
	v_lshlrev_b32_e32 v32, 16, v24
	v_pk_fma_f32 v[30:31], v[6:7], v[32:33], v[30:31]
	v_lshlrev_b32_e32 v16, 16, v25
	v_pk_mul_f32 v[28:29], v[30:31], v[28:29]
	v_and_b32_e32 v31, 0xffff0000, v21
	v_lshlrev_b32_e32 v30, 16, v21
	v_and_b32_e32 v21, 0xffff0000, v17
	v_and_b32_e32 v17, 0xffff0000, v25
	v_pk_fma_f32 v[16:17], v[8:9], v[16:17], v[20:21]
	v_and_b32_e32 v25, 0xffff0000, v18
	v_pk_mul_f32 v[20:21], v[16:17], v[30:31]
	v_lshlrev_b32_e32 v24, 16, v18
	v_and_b32_e32 v31, 0xffff0000, v26
	v_lshlrev_b32_e32 v30, 16, v26
	v_and_b32_e32 v17, 0xffff0000, v22
	v_lshlrev_b32_e32 v16, 16, v22
	v_pk_fma_f32 v[24:25], v[2:3], v[30:31], v[24:25]
	v_lshlrev_b32_e32 v22, 16, v19
	v_pk_mul_f32 v[24:25], v[24:25], v[16:17]
	v_and_b32_e32 v17, 0xffff0000, v23
	v_lshlrev_b32_e32 v16, 16, v23
	v_and_b32_e32 v23, 0xffff0000, v19
	v_and_b32_e32 v19, 0xffff0000, v27
	v_lshlrev_b32_e32 v18, 16, v27
	v_pk_fma_f32 v[18:19], v[4:5], v[18:19], v[22:23]
	s_nop 0
	v_pk_mul_f32 v[22:23], v[18:19], v[16:17]
	v_cvt_pk_bf16_f32 v16, v28, v29
	v_cvt_pk_bf16_f32 v17, v20, v21
	v_cvt_pk_bf16_f32 v18, v24, v25
	v_cvt_pk_bf16_f32 v19, v22, v23
	global_store_dwordx4 v[10:11], v[16:19], off
	v_lshl_add_u64 v[10:11], v[10:11], 0, s[10:11]
	s_nop 1
	s_branch .LBB0_497

.LBB0_591:
	v_add_u32_e32 v6, s30, v158
	v_ashrrev_i32_e32 v7, 31, v6
	v_lshlrev_b64 v[6:7], 9, v[6:7]
	v_lshl_add_u64 v[6:7], v[150:151], 0, v[6:7]
	v_lshl_add_u64 v[8:9], s[30:31], 1, v[152:153]
	global_load_dwordx4 v[142:145], v[6:7], off
	global_load_dwordx4 v[138:141], v[8:9], off
	s_movk_i32 s5, 0x110
	v_mul_lo_u32 v5, v158, s5
	v_and_b32_e32 v6, 64, v210
	v_add3_u32 v160, 0, v5, v0
	s_movk_i32 s4, 0x48
	v_xor_b32_e32 v5, 32, v210
	v_add_u32_e32 v6, 64, v6
	v_ashrrev_i32_e32 v154, 7, v157
	v_mul_lo_u32 v0, v4, s4
	s_movk_i32 s4, 0x2200
	v_cmp_lt_i32_e32 vcc, v5, v6
	v_bfe_u32 v3, v157, 5, 1
	v_add3_u32 v161, 0, v0, v2
	v_mul_lo_u32 v0, v154, s4
	v_cndmask_b32_e32 v5, v210, v5, vcc
	v_and_b32_e32 v147, 31, v157
	v_add_u32_e32 v0, 0, v0
	v_lshlrev_b32_e32 v156, 2, v5
	v_lshlrev_b32_e32 v5, 9, v154
	v_lshlrev_b32_e32 v146, 3, v3
	v_mad_u32_u24 v2, v147, s5, v0
	v_lshlrev_b32_e32 v4, 4, v3
	v_add3_u32 v0, v0, v5, v146
	v_mul_u32_u24_e32 v3, 0x48, v147
	s_lshl_b32 s20, s10, 5
	s_lshl_b32 s21, s10, 6
	v_mov_b32_e32 v148, 0
	s_lshl_b32 s6, s6, 7
	v_and_b32_e32 v155, 63, v157
	s_mov_b32 s14, 1
	s_mov_b32 s15, 32
	v_add_u32_e32 v162, s21, v158
	v_add_u32_e32 v163, s19, v158
	v_add_u32_e32 v164, s20, v158
	v_mov_b32_e32 v149, 0xf149f2ca
	v_add_u32_e32 v159, v2, v4
	v_add_u32_e32 v165, v0, v3
	v_mov_b32_e32 v50, 0
	v_mov_b32_e32 v51, v148
	v_mov_b32_e32 v52, v148
	v_mov_b32_e32 v53, v148
	v_mov_b32_e32 v54, v148
	v_mov_b32_e32 v55, v148
	v_mov_b32_e32 v56, v148
	v_mov_b32_e32 v57, v148
	v_mov_b32_e32 v58, v148
	v_mov_b32_e32 v59, v148
	v_mov_b32_e32 v60, v148
	v_mov_b32_e32 v61, v148
	v_mov_b32_e32 v62, v148
	v_mov_b32_e32 v63, v148
	v_mov_b32_e32 v64, v148
	v_mov_b32_e32 v65, v148
	v_mov_b32_e32 v34, 0
	v_mov_b32_e32 v35, v148
	v_mov_b32_e32 v36, v148
	v_mov_b32_e32 v37, v148
	v_mov_b32_e32 v38, v148
	v_mov_b32_e32 v39, v148
	v_mov_b32_e32 v40, v148
	v_mov_b32_e32 v41, v148
	v_mov_b32_e32 v42, v148
	v_mov_b32_e32 v43, v148
	v_mov_b32_e32 v44, v148
	v_mov_b32_e32 v45, v148
	v_mov_b32_e32 v46, v148
	v_mov_b32_e32 v47, v148
	v_mov_b32_e32 v48, v148
	v_mov_b32_e32 v49, v148
	v_mov_b32_e32 v18, 0
	v_mov_b32_e32 v19, v148
	v_mov_b32_e32 v20, v148
	v_mov_b32_e32 v21, v148
	v_mov_b32_e32 v22, v148
	v_mov_b32_e32 v23, v148
	v_mov_b32_e32 v24, v148
	v_mov_b32_e32 v25, v148
	v_mov_b32_e32 v26, v148
	v_mov_b32_e32 v27, v148
	v_mov_b32_e32 v28, v148
	v_mov_b32_e32 v29, v148
	v_mov_b32_e32 v30, v148
	v_mov_b32_e32 v31, v148
	v_mov_b32_e32 v32, v148
	v_mov_b32_e32 v33, v148
	v_mov_b32_e32 v2, 0
	v_mov_b32_e32 v3, v148
	v_mov_b32_e32 v4, v148
	v_mov_b32_e32 v5, v148
	v_mov_b32_e32 v6, v148
	v_mov_b32_e32 v7, v148
	v_mov_b32_e32 v8, v148
	v_mov_b32_e32 v9, v148
	v_mov_b32_e32 v10, v148
	v_mov_b32_e32 v11, v148
	v_mov_b32_e32 v12, v148
	v_mov_b32_e32 v13, v148
	v_mov_b32_e32 v14, v148
	v_mov_b32_e32 v15, v148
	v_mov_b32_e32 v16, v148
	v_mov_b32_e32 v17, v148
	v_readfirstlane_b32 s96, v202
	s_nop 3
	s_bfe_u32 s96, s96, 0x40006
	s_cmp_ge_u32 s96, 4
	s_cbranch_scc1 .Lgqa_prio_done
	s_setprio 1
.Lgqa_prio_done:
.LBB0_592:
	s_cmp_lt_u32 s14, s7
	s_cselect_b32 s4, 0, s7
	s_cselect_b32 s5, s24, s1
	s_lshl_b32 s4, s4, 5
	s_sub_i32 s4, s5, s4
	s_add_i32 s30, s15, s4
	s_add_i32 s4, s10, s14
	v_add_u32_e32 v66, s30, v158
	s_cmp_lt_u32 s4, s7
	v_ashrrev_i32_e32 v67, 31, v66
	s_cselect_b32 s4, 0, s7
	v_lshlrev_b64 v[66:67], 9, v[66:67]
	s_cselect_b32 s5, s24, s1
	s_lshl_b32 s4, s4, 5
	v_add_u32_e32 v166, 0x8800, v161
	v_add_u32_e32 v167, 0xac00, v161
	v_add_u32_e32 v168, 0xd000, v161
	v_add_u32_e32 v169, 0xf400, v161
	v_lshl_add_u64 v[66:67], v[150:151], 0, v[66:67]
	s_sub_i32 s4, s5, s4
	s_add_i32 s5, s20, s15
	s_waitcnt vmcnt(7)
	ds_write_b128 v160, v[118:121]
	s_waitcnt vmcnt(6)
	ds_write2_b64 v166, v[114:115], v[116:117] offset1:1
	s_waitcnt vmcnt(5)
	ds_write_b128 v160, v[126:129] offset:8704
	s_waitcnt vmcnt(4)
	ds_write2_b64 v167, v[122:123], v[124:125] offset1:1
	s_waitcnt vmcnt(3)
	ds_write_b128 v160, v[134:137] offset:17408
	s_waitcnt vmcnt(2)
	ds_write2_b64 v168, v[130:131], v[132:133] offset1:1
	s_waitcnt vmcnt(1)
	ds_write_b128 v160, v[142:145] offset:26112
	s_waitcnt vmcnt(0)
	ds_write2_b64 v169, v[138:139], v[140:141] offset1:1
	s_waitcnt lgkmcnt(0)
	s_barrier
	global_load_dwordx4 v[118:121], v[66:67], off
	v_lshl_add_u64 v[66:67], s[30:31], 1, v[152:153]
	s_add_i32 s30, s5, s4
	s_add_i32 s4, s4, s15
	global_load_dwordx4 v[114:117], v[66:67], off
	v_add_u32_e32 v66, s4, v164
	s_add_i32 s4, s11, s14
	s_cmp_lt_u32 s4, s7
	v_ashrrev_i32_e32 v67, 31, v66
	s_cselect_b32 s4, 0, s7
	v_lshlrev_b64 v[66:67], 9, v[66:67]
	s_cselect_b32 s5, s24, s1
	s_lshl_b32 s4, s4, 5
	v_lshl_add_u64 v[66:67], v[150:151], 0, v[66:67]
	s_sub_i32 s4, s5, s4
	s_add_i32 s5, s21, s15
	global_load_dwordx4 v[126:129], v[66:67], off
	v_lshl_add_u64 v[66:67], s[30:31], 1, v[152:153]
	s_add_i32 s30, s5, s4
	s_add_i32 s4, s4, s15
	global_load_dwordx4 v[122:125], v[66:67], off
	v_add_u32_e32 v66, s4, v162
	s_add_i32 s4, s18, s14
	s_cmp_lt_u32 s4, s7
	v_ashrrev_i32_e32 v67, 31, v66
	s_cselect_b32 s4, 0, s7
	v_lshlrev_b64 v[66:67], 9, v[66:67]
	s_cselect_b32 s5, s24, s1
	s_lshl_b32 s4, s4, 5
	v_lshl_add_u64 v[66:67], v[150:151], 0, v[66:67]
	s_sub_i32 s4, s5, s4
	s_add_i32 s5, s19, s15
	global_load_dwordx4 v[134:137], v[66:67], off
	v_lshl_add_u64 v[66:67], s[30:31], 1, v[152:153]
	s_add_i32 s30, s5, s4
	s_add_i32 s4, s4, s15
	global_load_dwordx4 v[130:133], v[66:67], off
	v_add_u32_e32 v66, s4, v163
	v_ashrrev_i32_e32 v67, 31, v66
	v_lshlrev_b64 v[66:67], 9, v[66:67]
	v_lshl_add_u64 v[66:67], v[150:151], 0, v[66:67]
	global_load_dwordx4 v[142:145], v[66:67], off
	v_lshl_add_u64 v[66:67], s[30:31], 1, v[152:153]
	global_load_dwordx4 v[138:141], v[66:67], off
	ds_read_b128 v[66:69], v159
	ds_read_b128 v[176:179], v159 offset:32
	s_waitcnt lgkmcnt(1)
	v_mfma_f32_32x32x16_bf16 v[66:81], v[66:69], v[110:113], 0
	v_mov_b32_e32 v0, v149
	v_mov_b32_e32 v175, v148
	s_add_i32 s15, s15, 32
	s_add_i32 s14, s14, 1
	s_cmp_lg_u32 s20, s15
	s_waitcnt lgkmcnt(0)
	v_mfma_f32_32x32x16_bf16 v[66:81], v[176:179], v[106:109], v[66:81]
	ds_read_b128 v[176:179], v159 offset:64
	s_waitcnt lgkmcnt(0)
	v_mfma_f32_32x32x16_bf16 v[66:81], v[176:179], v[102:105], v[66:81]
	ds_read_b128 v[176:179], v159 offset:96
	s_waitcnt lgkmcnt(0)
	v_mfma_f32_32x32x16_bf16 v[66:81], v[176:179], v[98:101], v[66:81]
	ds_read_b128 v[176:179], v159 offset:128
	s_waitcnt lgkmcnt(0)
	v_mfma_f32_32x32x16_bf16 v[66:81], v[176:179], v[94:97], v[66:81]
	ds_read_b128 v[176:179], v159 offset:160
	s_waitcnt lgkmcnt(0)
	v_mfma_f32_32x32x16_bf16 v[66:81], v[176:179], v[90:93], v[66:81]
	ds_read_b128 v[176:179], v159 offset:192
	s_waitcnt lgkmcnt(0)
	v_mfma_f32_32x32x16_bf16 v[66:81], v[176:179], v[86:89], v[66:81]
	ds_read_b128 v[176:179], v159 offset:224
	s_waitcnt lgkmcnt(0)
	v_mfma_f32_32x32x16_bf16 v[66:81], v[176:179], v[82:85], v[66:81]
	s_nop 11
	v_max_f32_e32 v148, v67, v67
	v_max_f32_e32 v149, v66, v66
	v_max_f32_e32 v148, v149, v148
	v_max3_f32 v148, v148, v68, v69
	v_max3_f32 v148, v148, v70, v71
	v_max3_f32 v148, v148, v72, v73
	v_max3_f32 v148, v148, v74, v75
	v_max3_f32 v148, v148, v76, v77
	v_max3_f32 v148, v148, v78, v79
	v_max3_f32 v148, v148, v80, v81
	ds_bpermute_b32 v149, v156, v148
	s_waitcnt lgkmcnt(0)
	v_max3_f32 v149, v0, v148, v149
	v_mov_b32_e32 v148, v81
	v_pk_mul_f32 v[176:177], v[148:149], s[28:29] op_sel_hi:[1,0]
	v_sub_f32_e32 v0, v0, v149
	v_fma_f32 v70, v70, s28, -v177
	v_exp_f32_e32 v81, v70
	v_fma_f32 v70, v71, s28, -v177
	v_exp_f32_e32 v178, v70
	v_fma_f32 v70, v72, s28, -v177
	v_exp_f32_e32 v179, v70
	v_fma_f32 v70, v73, s28, -v177
	v_exp_f32_e32 v73, v70
	v_fma_f32 v70, v74, s28, -v177
	v_exp_f32_e32 v74, v70
	v_fma_f32 v70, v75, s28, -v177
	v_exp_f32_e32 v75, v70
	v_fma_f32 v70, v76, s28, -v177
	v_fma_f32 v66, v66, s28, -v177
	v_exp_f32_e32 v76, v70
	v_fma_f32 v70, v77, s28, -v177
	v_exp_f32_e32 v66, v66
	v_fma_f32 v67, v67, s28, -v177
	v_exp_f32_e32 v77, v70
	v_fma_f32 v70, v78, s28, -v177
	v_exp_f32_e32 v67, v67
	v_fma_f32 v68, v68, s28, -v177
	v_exp_f32_e32 v78, v70
	v_fma_f32 v70, v79, s28, -v177
	v_exp_f32_e32 v68, v68
	v_fma_f32 v69, v69, s28, -v177
	v_exp_f32_e32 v79, v70
	v_fma_f32 v70, v80, s28, -v177
	v_exp_f32_e32 v69, v69
	v_exp_f32_e32 v80, v70
	v_sub_f32_e32 v70, v176, v177
	v_exp_f32_e32 v176, v70
	v_add_f32_e32 v70, 0, v66
	v_add_f32_e32 v70, v67, v70
	v_add_f32_e32 v70, v68, v70
	v_add_f32_e32 v70, v69, v70
	v_add_f32_e32 v70, v81, v70
	v_add_f32_e32 v70, v178, v70
	v_add_f32_e32 v70, v179, v70
	v_add_f32_e32 v70, v73, v70
	v_add_f32_e32 v70, v74, v70
	v_add_f32_e32 v70, v75, v70
	v_add_f32_e32 v70, v76, v70
	v_add_f32_e32 v70, v77, v70
	v_add_f32_e32 v70, v78, v70
	v_mul_f32_e32 v0, 0x3e0293ee, v0
	v_add_f32_e32 v70, v79, v70
	v_exp_f32_e32 v0, v0
	v_add_f32_e32 v70, v80, v70
	v_cvt_pk_bf16_f32 v73, v179, v73
	v_add_u32_e32 v179, 0x8800, v165
	v_add_f32_e32 v148, v176, v70
	v_cvt_pk_bf16_f32 v70, v66, v67
	v_cvt_pk_bf16_f32 v71, v68, v69
	v_cvt_pk_bf16_f32 v72, v81, v178
	v_cvt_pk_bf16_f32 v66, v74, v75
	v_cvt_pk_bf16_f32 v67, v76, v77
	v_cvt_pk_bf16_f32 v68, v78, v79
	v_cvt_pk_bf16_f32 v69, v80, v176
	ds_read2_b64 v[74:77], v179 offset1:2
	ds_read2_b64 v[78:81], v179 offset0:4 offset1:6
	v_pk_mul_f32 v[64:65], v[64:65], v[0:1] op_sel_hi:[1,0]
	v_pk_mul_f32 v[62:63], v[62:63], v[0:1] op_sel_hi:[1,0]
	v_pk_mul_f32 v[60:61], v[60:61], v[0:1] op_sel_hi:[1,0]
	v_pk_mul_f32 v[58:59], v[58:59], v[0:1] op_sel_hi:[1,0]
	v_pk_mul_f32 v[56:57], v[56:57], v[0:1] op_sel_hi:[1,0]
	v_pk_mul_f32 v[54:55], v[54:55], v[0:1] op_sel_hi:[1,0]
	v_pk_mul_f32 v[52:53], v[52:53], v[0:1] op_sel_hi:[1,0]
	v_pk_mul_f32 v[50:51], v[50:51], v[0:1] op_sel_hi:[1,0]
	v_add_u32_e32 v176, 0x9000, v165
	v_pk_mul_f32 v[48:49], v[48:49], v[0:1] op_sel_hi:[1,0]
	s_waitcnt lgkmcnt(1)
	v_mfma_f32_32x32x16_bf16 v[50:65], v[74:77], v[70:73], v[50:65]
	ds_read2_b64 v[74:77], v176 offset0:32 offset1:34
	v_mul_f32_e64 v46, v46, v0
	v_mul_f32_e64 v47, v47, v0
	v_mul_f32_e64 v44, v44, v0
	v_mul_f32_e64 v45, v45, v0
	v_pk_mul_f32 v[42:43], v[42:43], v[0:1] op_sel_hi:[1,0]
	v_pk_mul_f32 v[40:41], v[40:41], v[0:1] op_sel_hi:[1,0]
	v_pk_mul_f32 v[38:39], v[38:39], v[0:1] op_sel_hi:[1,0]
	v_pk_mul_f32 v[36:37], v[36:37], v[0:1] op_sel_hi:[1,0]
	v_pk_mul_f32 v[34:35], v[34:35], v[0:1] op_sel_hi:[1,0]
	v_add_u32_e32 v177, 0x9800, v165
	v_pk_mul_f32 v[32:33], v[32:33], v[0:1] op_sel_hi:[1,0]
	s_waitcnt lgkmcnt(0)
	v_mfma_f32_32x32x16_bf16 v[34:49], v[74:77], v[70:73], v[34:49]
	ds_read2_b64 v[74:77], v176 offset0:36 offset1:38
	v_mul_f32_e64 v30, v30, v0
	v_mul_f32_e64 v31, v31, v0
	v_mul_f32_e64 v28, v28, v0
	v_mul_f32_e64 v29, v29, v0
	v_pk_mul_f32 v[26:27], v[26:27], v[0:1] op_sel_hi:[1,0]
	v_pk_mul_f32 v[24:25], v[24:25], v[0:1] op_sel_hi:[1,0]
	v_pk_mul_f32 v[22:23], v[22:23], v[0:1] op_sel_hi:[1,0]
	v_pk_mul_f32 v[20:21], v[20:21], v[0:1] op_sel_hi:[1,0]
	s_waitcnt lgkmcnt(0)
	v_mfma_f32_32x32x16_bf16 v[34:49], v[74:77], v[66:69], v[34:49]
	ds_read2_b64 v[74:77], v177 offset0:64 offset1:66
	v_mul_f32_e64 v18, v18, v0
	v_mul_f32_e64 v19, v19, v0
	v_add_u32_e32 v178, 0xa000, v165
	v_mul_f32_e64 v16, v16, v0
	v_mul_f32_e64 v17, v17, v0
	v_pk_mul_f32 v[14:15], v[14:15], v[0:1] op_sel_hi:[1,0]
	v_pk_mul_f32 v[12:13], v[12:13], v[0:1] op_sel_hi:[1,0]
	v_pk_mul_f32 v[10:11], v[10:11], v[0:1] op_sel_hi:[1,0]
	s_waitcnt lgkmcnt(0)
	v_mfma_f32_32x32x16_bf16 v[18:33], v[74:77], v[70:73], v[18:33]
	ds_read2_b64 v[74:77], v177 offset0:68 offset1:70
	v_mul_f32_e64 v8, v8, v0
	v_mul_f32_e64 v9, v9, v0
	v_mul_f32_e64 v6, v6, v0
	v_mul_f32_e64 v7, v7, v0
	v_pk_mul_f32 v[4:5], v[4:5], v[0:1] op_sel_hi:[1,0]
	v_pk_mul_f32 v[2:3], v[2:3], v[0:1] op_sel_hi:[1,0]
	v_fmac_f32_e32 v148, v175, v0
	s_waitcnt lgkmcnt(0)
	v_mfma_f32_32x32x16_bf16 v[18:33], v[74:77], v[66:69], v[18:33]
	ds_read2_b64 v[74:77], v178 offset0:96 offset1:98
	s_waitcnt lgkmcnt(0)
	v_mfma_f32_32x32x16_bf16 v[2:17], v[74:77], v[70:73], v[2:17]
	ds_read2_b64 v[70:73], v178 offset0:100 offset1:102
	s_waitcnt lgkmcnt(0)
	s_barrier
	v_mfma_f32_32x32x16_bf16 v[50:65], v[78:81], v[66:69], v[50:65]
	v_mfma_f32_32x32x16_bf16 v[2:17], v[70:73], v[66:69], v[2:17]
	s_cbranch_scc1 .LBB0_592
	s_setprio 0
	s_waitcnt vmcnt(7)
	ds_write_b128 v160, v[118:121]
	s_waitcnt vmcnt(6)
	ds_write2_b64 v166, v[114:115], v[116:117] offset1:1
	s_waitcnt vmcnt(5)
	ds_write_b128 v160, v[126:129] offset:8704
	s_waitcnt vmcnt(4)
	ds_write2_b64 v167, v[122:123], v[124:125] offset1:1
	s_waitcnt vmcnt(3)
	ds_write_b128 v160, v[134:137] offset:17408
	s_waitcnt vmcnt(2)
	ds_write2_b64 v168, v[130:131], v[132:133] offset1:1
	s_waitcnt vmcnt(1)
	ds_write_b128 v160, v[142:145] offset:26112
	s_waitcnt vmcnt(0)
	ds_write2_b64 v169, v[138:139], v[140:141] offset1:1
	s_waitcnt lgkmcnt(0)
	s_barrier
	ds_read_b128 v[66:69], v159
	ds_read_b128 v[114:117], v159 offset:32
	s_waitcnt lgkmcnt(1)
	v_mfma_f32_32x32x16_bf16 v[66:81], v[66:69], v[110:113], 0
	v_readlane_b32 s1, v253, 17
	s_mov_b32 s4, 0xf149f2ca
	s_waitcnt lgkmcnt(0)
	v_mfma_f32_32x32x16_bf16 v[66:81], v[114:117], v[106:109], v[66:81]
	ds_read_b128 v[106:109], v159 offset:64
	ds_read_b128 v[110:113], v159 offset:96
	s_waitcnt lgkmcnt(1)
	v_mfma_f32_32x32x16_bf16 v[66:81], v[106:109], v[102:105], v[66:81]
	s_waitcnt lgkmcnt(0)
	v_mfma_f32_32x32x16_bf16 v[66:81], v[110:113], v[98:101], v[66:81]
	ds_read_b128 v[98:101], v159 offset:128
	ds_read_b128 v[102:105], v159 offset:160
	s_waitcnt lgkmcnt(1)
	v_mfma_f32_32x32x16_bf16 v[66:81], v[98:101], v[94:97], v[66:81]
	v_ashrrev_i32_e32 v100, 6, v157
	s_waitcnt lgkmcnt(0)
	v_mfma_f32_32x32x16_bf16 v[66:81], v[102:105], v[90:93], v[66:81]
	ds_read_b128 v[90:93], v159 offset:192
	ds_read_b128 v[94:97], v159 offset:224
	s_waitcnt lgkmcnt(1)
	v_mfma_f32_32x32x16_bf16 v[66:81], v[90:93], v[86:89], v[66:81]
	ds_read2_b64 v[86:89], v179 offset1:2
	s_waitcnt lgkmcnt(1)
	v_mfma_f32_32x32x16_bf16 v[66:81], v[94:97], v[82:85], v[66:81]
	ds_read2_b64 v[90:93], v179 offset0:4 offset1:6
	ds_read2_b64 v[94:97], v176 offset0:32 offset1:34
	s_nop 9
	v_max_f32_e32 v0, v67, v67
	v_max_f32_e32 v82, v66, v66
	v_max_f32_e32 v0, v82, v0
	v_max3_f32 v0, v0, v68, v69
	v_max3_f32 v0, v0, v70, v71
	v_max3_f32 v0, v0, v72, v73
	v_max3_f32 v0, v0, v74, v75
	v_max3_f32 v0, v0, v76, v77
	v_max3_f32 v0, v0, v78, v79
	v_max3_f32 v0, v0, v80, v81
	ds_bpermute_b32 v83, v156, v0
	v_mov_b32_e32 v84, v81
	v_and_b32_e32 v82, 1, v100
	s_waitcnt lgkmcnt(0)
	v_max3_f32 v85, v149, v0, v83
	v_sub_f32_e32 v0, v149, v85
	v_pk_mul_f32 v[98:99], v[84:85], s[28:29] op_sel_hi:[1,0]
	v_mul_f32_e32 v0, 0x3e0293ee, v0
	v_fma_f32 v66, v66, s28, -v99
	v_fma_f32 v67, v67, s28, -v99
	v_fma_f32 v68, v68, s28, -v99
	v_fma_f32 v69, v69, s28, -v99
	v_fma_f32 v70, v70, s28, -v99
	v_fma_f32 v71, v71, s28, -v99
	v_fma_f32 v72, v72, s28, -v99
	v_fma_f32 v73, v73, s28, -v99
	v_fma_f32 v74, v74, s28, -v99
	v_fma_f32 v75, v75, s28, -v99
	v_fma_f32 v76, v76, s28, -v99
	v_fma_f32 v77, v77, s28, -v99
	v_fma_f32 v78, v78, s28, -v99
	v_fma_f32 v79, v79, s28, -v99
	v_fma_f32 v80, v80, s28, -v99
	v_sub_f32_e32 v81, v98, v99
	v_exp_f32_e32 v0, v0
	v_exp_f32_e32 v83, v66
	v_exp_f32_e32 v84, v67
	v_exp_f32_e32 v98, v68
	v_exp_f32_e32 v99, v69
	v_exp_f32_e32 v101, v70
	v_exp_f32_e32 v102, v71
	v_exp_f32_e32 v103, v72
	v_exp_f32_e32 v104, v73
	v_exp_f32_e32 v105, v74
	v_exp_f32_e32 v106, v75
	v_exp_f32_e32 v107, v76
	v_exp_f32_e32 v108, v77
	v_pk_mul_f32 v[48:49], v[48:49], v[0:1] op_sel_hi:[1,0]
	v_pk_mul_f32 v[46:47], v[46:47], v[0:1] op_sel_hi:[1,0]
	v_cvt_pk_bf16_f32 v66, v83, v84
	v_cvt_pk_bf16_f32 v67, v98, v99
	v_cvt_pk_bf16_f32 v68, v101, v102
	v_cvt_pk_bf16_f32 v69, v103, v104
	v_pk_mul_f32 v[44:45], v[44:45], v[0:1] op_sel_hi:[1,0]
	v_pk_mul_f32 v[42:43], v[42:43], v[0:1] op_sel_hi:[1,0]
	v_pk_mul_f32 v[40:41], v[40:41], v[0:1] op_sel_hi:[1,0]
	v_pk_mul_f32 v[38:39], v[38:39], v[0:1] op_sel_hi:[1,0]
	v_pk_mul_f32 v[36:37], v[36:37], v[0:1] op_sel_hi:[1,0]
	v_pk_mul_f32 v[34:35], v[34:35], v[0:1] op_sel_hi:[1,0]
	ds_read2_b64 v[74:77], v176 offset0:36 offset1:38
	v_exp_f32_e32 v109, v78
	v_exp_f32_e32 v110, v79
	v_exp_f32_e32 v111, v80
	v_exp_f32_e32 v112, v81
	v_mfma_f32_32x32x16_bf16 v[34:49], v[94:97], v[66:69], v[34:49]
	ds_read2_b64 v[78:81], v177 offset0:64 offset1:66
	v_cvt_pk_bf16_f32 v70, v105, v106
	v_cvt_pk_bf16_f32 v71, v107, v108
	v_cvt_pk_bf16_f32 v72, v109, v110
	v_cvt_pk_bf16_f32 v73, v111, v112
	v_pk_mul_f32 v[32:33], v[32:33], v[0:1] op_sel_hi:[1,0]
	v_pk_mul_f32 v[30:31], v[30:31], v[0:1] op_sel_hi:[1,0]
	v_pk_mul_f32 v[28:29], v[28:29], v[0:1] op_sel_hi:[1,0]
	v_pk_mul_f32 v[26:27], v[26:27], v[0:1] op_sel_hi:[1,0]
	v_pk_mul_f32 v[24:25], v[24:25], v[0:1] op_sel_hi:[1,0]
	v_pk_mul_f32 v[22:23], v[22:23], v[0:1] op_sel_hi:[1,0]
	v_pk_mul_f32 v[20:21], v[20:21], v[0:1] op_sel_hi:[1,0]
	v_pk_mul_f32 v[18:19], v[18:19], v[0:1] op_sel_hi:[1,0]
	s_waitcnt lgkmcnt(1)
	v_mfma_f32_32x32x16_bf16 v[34:49], v[74:77], v[70:73], v[34:49]
	ds_read2_b64 v[74:77], v177 offset0:68 offset1:70
	v_mul_f32_e64 v64, v64, v0
	v_mul_f32_e64 v65, v65, v0
	v_mul_f32_e64 v62, v62, v0
	v_mul_f32_e64 v63, v63, v0
	v_pk_mul_f32 v[60:61], v[60:61], v[0:1] op_sel_hi:[1,0]
	v_pk_mul_f32 v[58:59], v[58:59], v[0:1] op_sel_hi:[1,0]
	v_pk_mul_f32 v[56:57], v[56:57], v[0:1] op_sel_hi:[1,0]
	v_pk_mul_f32 v[54:55], v[54:55], v[0:1] op_sel_hi:[1,0]
	s_waitcnt lgkmcnt(1)
	v_mfma_f32_32x32x16_bf16 v[18:33], v[78:81], v[66:69], v[18:33]
	v_add_f32_e32 v78, 0, v83
	v_add_f32_e32 v78, v84, v78
	v_add_f32_e32 v78, v98, v78
	v_add_f32_e32 v78, v99, v78
	v_add_f32_e32 v83, v101, v78
	ds_read2_b64 v[78:81], v178 offset0:96 offset1:98
	v_pk_mul_f32 v[52:53], v[52:53], v[0:1] op_sel_hi:[1,0]
	s_waitcnt lgkmcnt(1)
	v_mfma_f32_32x32x16_bf16 v[18:33], v[74:77], v[70:73], v[18:33]
	v_add_f32_e32 v74, v102, v83
	v_add_f32_e32 v74, v103, v74
	v_add_f32_e32 v74, v104, v74
	v_add_f32_e32 v74, v105, v74
	v_mul_f32_e64 v50, v50, v0
	v_mul_f32_e64 v51, v51, v0
	v_add_f32_e32 v74, v106, v74
	v_pk_mul_f32 v[16:17], v[16:17], v[0:1] op_sel_hi:[1,0]
	v_mfma_f32_32x32x16_bf16 v[50:65], v[86:89], v[66:69], v[50:65]
	v_mul_f32_e64 v14, v14, v0
	v_mul_f32_e64 v15, v15, v0
	v_mul_f32_e64 v12, v12, v0
	v_mul_f32_e64 v13, v13, v0
	v_mul_f32_e64 v10, v10, v0
	v_mul_f32_e64 v11, v11, v0
	v_pk_mul_f32 v[8:9], v[8:9], v[0:1] op_sel_hi:[1,0]
	v_pk_mul_f32 v[6:7], v[6:7], v[0:1] op_sel_hi:[1,0]
	v_pk_mul_f32 v[4:5], v[4:5], v[0:1] op_sel_hi:[1,0]
	v_pk_mul_f32 v[2:3], v[2:3], v[0:1] op_sel_hi:[1,0]
	v_add_f32_e32 v83, v107, v74
	ds_read2_b64 v[74:77], v178 offset0:100 offset1:102
	s_waitcnt lgkmcnt(1)
	v_mfma_f32_32x32x16_bf16 v[2:17], v[78:81], v[66:69], v[2:17]
	v_add_f32_e32 v66, v108, v83
	v_add_f32_e32 v66, v109, v66
	v_add_f32_e32 v66, v110, v66
	v_add_f32_e32 v66, v111, v66
	v_add_f32_e32 v66, v112, v66
	v_fmac_f32_e32 v66, v148, v0
	ds_bpermute_b32 v0, v156, v66
	v_mfma_f32_32x32x16_bf16 v[50:65], v[90:93], v[70:73], v[50:65]
	v_lshlrev_b32_e32 v67, 2, v155
	s_waitcnt lgkmcnt(0)
	s_barrier
	v_add_f32_e32 v0, v66, v0
	v_lshlrev_b32_e32 v66, 9, v100
	v_add3_u32 v66, s1, v66, v67
	ds_write2st64_b32 v66, v85, v0 offset1:1
	v_lshlrev_b32_e32 v0, 14, v100
	v_add3_u32 v0, 0, v0, v67
	v_mfma_f32_32x32x16_bf16 v[2:17], v[74:77], v[70:73], v[2:17]
	s_nop 1
	ds_write2st64_b32 v0, v50, v51 offset1:1
	ds_write2st64_b32 v0, v52, v53 offset0:2 offset1:3
	ds_write2st64_b32 v0, v54, v55 offset0:4 offset1:5
	ds_write2st64_b32 v0, v56, v57 offset0:6 offset1:7
	ds_write2st64_b32 v0, v58, v59 offset0:8 offset1:9
	ds_write2st64_b32 v0, v60, v61 offset0:10 offset1:11
	ds_write2st64_b32 v0, v62, v63 offset0:12 offset1:13
	ds_write2st64_b32 v0, v64, v65 offset0:14 offset1:15
	ds_write2st64_b32 v0, v34, v35 offset0:16 offset1:17
	ds_write2st64_b32 v0, v36, v37 offset0:18 offset1:19
	ds_write2st64_b32 v0, v38, v39 offset0:20 offset1:21
	ds_write2st64_b32 v0, v40, v41 offset0:22 offset1:23
	ds_write2st64_b32 v0, v42, v43 offset0:24 offset1:25
	ds_write2st64_b32 v0, v44, v45 offset0:26 offset1:27
	ds_write2st64_b32 v0, v46, v47 offset0:28 offset1:29
	ds_write2st64_b32 v0, v48, v49 offset0:30 offset1:31
	ds_write2st64_b32 v0, v18, v19 offset0:32 offset1:33
	ds_write2st64_b32 v0, v20, v21 offset0:34 offset1:35
	ds_write2st64_b32 v0, v22, v23 offset0:36 offset1:37
	ds_write2st64_b32 v0, v24, v25 offset0:38 offset1:39
	ds_write2st64_b32 v0, v26, v27 offset0:40 offset1:41
	ds_write2st64_b32 v0, v28, v29 offset0:42 offset1:43
	ds_write2st64_b32 v0, v30, v31 offset0:44 offset1:45
	ds_write2st64_b32 v0, v32, v33 offset0:46 offset1:47
	ds_write2st64_b32 v0, v2, v3 offset0:48 offset1:49
	ds_write2st64_b32 v0, v4, v5 offset0:50 offset1:51
	ds_write2st64_b32 v0, v6, v7 offset0:52 offset1:53
	ds_write2st64_b32 v0, v8, v9 offset0:54 offset1:55
	ds_write2st64_b32 v0, v10, v11 offset0:56 offset1:57
	ds_write2st64_b32 v0, v12, v13 offset0:58 offset1:59
	ds_write2st64_b32 v0, v14, v15 offset0:60 offset1:61
	ds_write2st64_b32 v0, v16, v17 offset0:62 offset1:63
	v_lshlrev_b32_e32 v0, 9, v82
	v_add3_u32 v0, s1, v0, v67
	s_waitcnt lgkmcnt(0)
	s_barrier
	ds_read2st64_b32 v[4:5], v0 offset1:1
	ds_read2st64_b32 v[6:7], v0 offset0:4 offset1:5
	ds_read2st64_b32 v[8:9], v0 offset0:8 offset1:9
	ds_read2st64_b32 v[10:11], v0 offset0:12 offset1:13
	s_mov_b32 s1, s31
	s_lshl_b64 s[0:1], s[0:1], 11
	s_waitcnt lgkmcnt(2)
	v_max3_f32 v0, v4, s4, v6
	s_add_u32 s4, s80, s0
	s_waitcnt lgkmcnt(0)
	v_max3_f32 v0, v0, v8, v10
	v_sub_f32_e32 v2, v4, v0
	v_mul_f32_e32 v2, 0x3e0293ee, v2
	v_exp_f32_e32 v3, v2
	v_sub_f32_e32 v2, v6, v0
	v_mul_f32_e32 v2, 0x3e0293ee, v2
	v_exp_f32_e32 v2, v2
	v_mov_b32_e32 v4, v7
	s_addc_u32 s5, s81, s1
	v_pk_mul_f32 v[6:7], v[4:5], v[2:3]
	v_sub_f32_e32 v4, v8, v0
	v_sub_f32_e32 v0, v10, v0
	v_mul_f32_e32 v4, 0x3e0293ee, v4
	v_mul_f32_e32 v0, 0x3e0293ee, v0
	v_exp_f32_e32 v5, v4
	v_exp_f32_e32 v4, v0
	v_add_f32_e32 v0, 0, v7
	v_mov_b32_e32 v8, v11
	v_add_f32_e32 v0, v6, v0
	v_pk_mul_f32 v[6:7], v[8:9], v[4:5]
	s_nop 0
	v_add_f32_e32 v0, v7, v0
	v_add_f32_e32 v0, v6, v0
	v_div_scale_f32 v6, s[0:1], v0, v0, 1.0
	v_rcp_f32_e32 v7, v6
	s_lshl_b32 s0, s6, 1
	s_add_u32 s0, s4, s0
	s_addc_u32 s1, s5, 0
	v_fma_f32 v8, -v6, v7, 1.0
	v_fmac_f32_e32 v7, v8, v7
	v_div_scale_f32 v8, vcc, 1.0, v0, 1.0
	v_mul_f32_e32 v9, v8, v7
	v_fma_f32 v10, -v6, v9, v8
	v_fmac_f32_e32 v9, v10, v7
	v_fma_f32 v6, -v6, v9, v8
	v_div_fmas_f32 v6, v6, v7, v9
	v_div_fixup_f32 v0, v6, v0, 1.0
	v_lshl_add_u32 v6, v82, 14, 0
	v_lshlrev_b32_e32 v7, 12, v154
	v_add3_u32 v7, v6, v7, v67
	ds_read2st64_b32 v[8:9], v7 offset1:1
	ds_read2st64_b32 v[10:11], v7 offset0:128 offset1:129
	v_mov_b32_e32 v6, v3
	v_add_u32_e32 v24, 0x10000, v7
	v_add_u32_e32 v25, 0x18000, v7
	v_add_u32_e32 v27, 0x10100, v7
	v_add_u32_e32 v28, 0x18100, v7
	ds_read2st64_b32 v[12:13], v7 offset0:2 offset1:3
	ds_read2st64_b32 v[14:15], v7 offset0:4 offset1:5
	ds_read2st64_b32 v[16:17], v7 offset0:6 offset1:7
	s_waitcnt lgkmcnt(4)
	v_pk_fma_f32 v[8:9], v[8:9], v[6:7], 0 op_sel_hi:[1,0,0]
	v_add_u32_e32 v31, 0x18300, v7
	ds_read2st64_b32 v[18:19], v7 offset0:130 offset1:131
	ds_read2st64_b32 v[20:21], v7 offset0:132 offset1:133
	ds_read2st64_b32 v[22:23], v7 offset0:134 offset1:135
	s_waitcnt lgkmcnt(6)
	v_pk_fma_f32 v[8:9], v[10:11], v[2:3], v[8:9] op_sel_hi:[1,0,1]
	v_mov_b32_e32 v10, v5
	v_add_u32_e32 v3, 0x10200, v7
	v_add_u32_e32 v5, 0x18200, v7
	v_add_u32_e32 v11, 0x10300, v7
	ds_read_b32 v24, v24
	ds_read_b32 v26, v25
	ds_read_b32 v25, v27
	ds_read_b32 v27, v28
	ds_read_b32 v28, v3
	ds_read_b32 v30, v5
	ds_read_b32 v29, v11
	ds_read_b32 v31, v31
	s_waitcnt lgkmcnt(13)
	v_pk_fma_f32 v[12:13], v[6:7], v[12:13], 0 op_sel_hi:[0,1,0]
	s_waitcnt lgkmcnt(5)
	v_pk_fma_f32 v[8:9], v[10:11], v[24:25], v[8:9] op_sel_hi:[0,1,1]
	v_pk_fma_f32 v[12:13], v[2:3], v[18:19], v[12:13] op_sel_hi:[0,1,1]
	v_add_u32_e32 v3, 0x10400, v7
	v_pk_fma_f32 v[14:15], v[6:7], v[14:15], 0 op_sel_hi:[0,1,0]
	s_waitcnt lgkmcnt(4)
	v_pk_fma_f32 v[8:9], v[4:5], v[26:27], v[8:9] op_sel_hi:[0,1,1]
	s_waitcnt lgkmcnt(1)
	v_pk_fma_f32 v[12:13], v[10:11], v[28:29], v[12:13] op_sel_hi:[0,1,1]
	v_add_u32_e32 v11, 0x10500, v7
	v_add_u32_e32 v24, 0x18500, v7
	v_pk_fma_f32 v[14:15], v[2:3], v[20:21], v[14:15] op_sel_hi:[0,1,1]
	v_add_u32_e32 v25, 0x10600, v7
	v_add_u32_e32 v26, 0x18600, v7
	v_add_u32_e32 v27, 0x10700, v7
	s_waitcnt lgkmcnt(0)
	v_pk_fma_f32 v[12:13], v[4:5], v[30:31], v[12:13] op_sel_hi:[0,1,1]
	v_add_u32_e32 v5, 0x18400, v7
	v_add_u32_e32 v28, 0x18700, v7
	ds_read_b32 v18, v3
	ds_read_b32 v20, v5
	ds_read_b32 v19, v11
	ds_read_b32 v21, v24
	ds_read_b32 v24, v25
	ds_read_b32 v26, v26
	ds_read_b32 v25, v27
	ds_read_b32 v27, v28
	s_waitcnt lgkmcnt(5)
	v_pk_fma_f32 v[14:15], v[10:11], v[18:19], v[14:15] op_sel_hi:[0,1,1]
	s_waitcnt lgkmcnt(4)
	v_pk_fma_f32 v[14:15], v[4:5], v[20:21], v[14:15] op_sel_hi:[0,1,1]
	ds_read2st64_b32 v[18:19], v7 offset0:8 offset1:9
	ds_read2st64_b32 v[20:21], v7 offset0:136 offset1:137
	v_pk_fma_f32 v[16:17], v[6:7], v[16:17], 0 op_sel_hi:[0,1,0]
	v_pk_fma_f32 v[16:17], v[2:3], v[22:23], v[16:17] op_sel_hi:[0,1,1]
	s_waitcnt lgkmcnt(3)
	v_pk_fma_f32 v[16:17], v[10:11], v[24:25], v[16:17] op_sel_hi:[0,1,1]
	s_waitcnt lgkmcnt(2)
	v_pk_fma_f32 v[16:17], v[4:5], v[26:27], v[16:17] op_sel_hi:[0,1,1]
	v_add_u32_e32 v3, 0x10800, v7
	v_add_u32_e32 v35, 0x18900, v7
	ds_read2st64_b32 v[22:23], v7 offset0:10 offset1:11
	ds_read2st64_b32 v[24:25], v7 offset0:12 offset1:13
	ds_read2st64_b32 v[26:27], v7 offset0:14 offset1:15
	s_waitcnt lgkmcnt(4)
	v_pk_fma_f32 v[18:19], v[6:7], v[18:19], 0 op_sel_hi:[0,1,0]
	v_add_u32_e32 v36, 0x10a00, v7
	v_add_u32_e32 v37, 0x18a00, v7
	v_add_u32_e32 v39, 0x10b00, v7
	v_add_u32_e32 v5, 0x18800, v7
	v_add_u32_e32 v11, 0x10900, v7
	ds_read2st64_b32 v[28:29], v7 offset0:138 offset1:139
	ds_read2st64_b32 v[30:31], v7 offset0:140 offset1:141
	ds_read2st64_b32 v[32:33], v7 offset0:142 offset1:143
	s_waitcnt lgkmcnt(6)
	v_pk_fma_f32 v[18:19], v[2:3], v[20:21], v[18:19] op_sel_hi:[0,1,1]
	v_add_u32_e32 v40, 0x18b00, v7
	ds_read_b32 v20, v3
	ds_read_b32 v34, v5
	ds_read_b32 v21, v11
	ds_read_b32 v35, v35
	ds_read_b32 v36, v36
	ds_read_b32 v38, v37
	ds_read_b32 v37, v39
	ds_read_b32 v39, v40
	s_waitcnt lgkmcnt(5)
	v_pk_fma_f32 v[18:19], v[10:11], v[20:21], v[18:19] op_sel_hi:[0,1,1]
	v_pk_fma_f32 v[20:21], v[6:7], v[22:23], 0 op_sel_hi:[0,1,0]
	v_pk_fma_f32 v[20:21], v[2:3], v[28:29], v[20:21] op_sel_hi:[0,1,1]
	v_add_u32_e32 v3, 0x10c00, v7
	v_pk_fma_f32 v[22:23], v[6:7], v[24:25], 0 op_sel_hi:[0,1,0]
	s_waitcnt lgkmcnt(4)
	v_pk_fma_f32 v[18:19], v[4:5], v[34:35], v[18:19] op_sel_hi:[0,1,1]
	s_waitcnt lgkmcnt(1)
	v_pk_fma_f32 v[20:21], v[10:11], v[36:37], v[20:21] op_sel_hi:[0,1,1]
	v_add_u32_e32 v29, 0x18d00, v7
	v_pk_fma_f32 v[22:23], v[2:3], v[30:31], v[22:23] op_sel_hi:[0,1,1]
	v_add_u32_e32 v30, 0x10e00, v7
	v_add_u32_e32 v31, 0x18e00, v7
	v_add_u32_e32 v35, 0x10f00, v7
	s_waitcnt lgkmcnt(0)
	v_pk_fma_f32 v[20:21], v[4:5], v[38:39], v[20:21] op_sel_hi:[0,1,1]
	v_add_u32_e32 v5, 0x18c00, v7
	v_add_u32_e32 v11, 0x10d00, v7
	v_add_u32_e32 v7, 0x18f00, v7
	ds_read_b32 v24, v3
	ds_read_b32 v28, v5
	ds_read_b32 v25, v11
	ds_read_b32 v29, v29
	ds_read_b32 v30, v30
	ds_read_b32 v34, v31
	ds_read_b32 v31, v35
	ds_read_b32 v35, v7
	v_pk_fma_f32 v[6:7], v[6:7], v[26:27], 0 op_sel_hi:[0,1,0]
	v_pk_fma_f32 v[2:3], v[2:3], v[32:33], v[6:7] op_sel_hi:[0,1,1]
	s_waitcnt lgkmcnt(5)
	v_pk_fma_f32 v[22:23], v[10:11], v[24:25], v[22:23] op_sel_hi:[0,1,1]
	s_waitcnt lgkmcnt(1)
	v_pk_fma_f32 v[2:3], v[10:11], v[30:31], v[2:3] op_sel_hi:[0,1,1]
	v_pk_fma_f32 v[22:23], v[4:5], v[28:29], v[22:23] op_sel_hi:[0,1,1]
	s_waitcnt lgkmcnt(0)
	v_pk_fma_f32 v[2:3], v[4:5], v[34:35], v[2:3] op_sel_hi:[0,1,1]
	v_pk_mul_f32 v[8:9], v[8:9], v[0:1] op_sel_hi:[1,0]
	v_pk_mul_f32 v[12:13], v[0:1], v[12:13] op_sel_hi:[0,1]
	v_pk_mul_f32 v[14:15], v[0:1], v[14:15] op_sel_hi:[0,1]
	v_pk_mul_f32 v[16:17], v[0:1], v[16:17] op_sel_hi:[0,1]
	v_pk_mul_f32 v[18:19], v[0:1], v[18:19] op_sel_hi:[0,1]
	v_pk_mul_f32 v[20:21], v[0:1], v[20:21] op_sel_hi:[0,1]
	v_pk_mul_f32 v[22:23], v[0:1], v[22:23] op_sel_hi:[0,1]
	v_pk_mul_f32 v[2:3], v[0:1], v[2:3] op_sel_hi:[0,1]
	v_lshlrev_b32_e32 v0, 11, v147
	v_lshl_or_b32 v0, v82, 16, v0
	v_lshlrev_b32_e32 v6, 5, v154
	v_lshl_add_u64 v[4:5], s[0:1], 0, v[0:1]
	v_ashrrev_i32_e32 v7, 31, v6
	v_lshl_add_u64 v[4:5], v[6:7], 1, v[4:5]
	v_mov_b32_e32 v147, v1
	v_lshl_add_u64 v[4:5], v[4:5], 0, v[146:147]
	s_mov_b64 s[0:1], 0x4328400
	v_lshl_add_u64 v[6:7], v[4:5], 0, s[0:1]
	s_mov_b32 s0, 0x4328000
	v_add_co_u32_e32 v4, vcc, s0, v4
	v_cvt_pk_bf16_f32 v8, v8, v9
	v_cvt_pk_bf16_f32 v9, v12, v13
	v_addc_co_u32_e32 v5, vcc, 0, v5, vcc
	global_store_dwordx2 v[4:5], v[8:9], off offset:1024
	v_cvt_pk_bf16_f32 v4, v14, v15
	v_cvt_pk_bf16_f32 v5, v16, v17
	global_store_dwordx2 v[6:7], v[4:5], off offset:16
	v_cvt_pk_bf16_f32 v4, v18, v19
	v_cvt_pk_bf16_f32 v5, v20, v21
	global_store_dwordx2 v[6:7], v[4:5], off offset:32
	v_cvt_pk_bf16_f32 v4, v22, v23
	v_cvt_pk_bf16_f32 v5, v2, v3
	global_store_dwordx2 v[6:7], v[4:5], off offset:48
	s_barrier
	s_mov_b64 s[0:1], 0
